# GEMM loop: as previous best plus removal of the mid-segment lgkmcnt(0) between B and A fragment reads
# speedup vs baseline: 1.0015x; 1.0015x over previous
.LBB0_176:
	s_mov_b32 m0, s55
	s_nop 0
	global_load_lds_dwordx4 v194, s[100:101]
	s_mov_b32 m0, s67
	s_nop 0
	global_load_lds_dwordx4 v196, s[100:101]
	v_add_u32_e32 v130, 0x10000, v243
	v_add_u32_e32 v142, 0x14000, v243
	ds_read_b128 v[146:149], v130
	ds_read_b128 v[150:153], v130 offset:1024
	ds_read_b128 v[154:157], v130 offset:2048
	ds_read_b128 v[158:161], v130 offset:3072
	ds_read_b128 v[130:133], v142
	ds_read_b128 v[134:137], v142 offset:1024
	ds_read_b128 v[138:141], v142 offset:2048
	ds_read_b128 v[142:145], v142 offset:3072
	v_lshl_add_u64 v[246:247], v[234:235], 0, s[80:81]
	s_add_i32 m0, s8, 0xc000
	ds_read_b128 v[174:177], v244
	ds_read_b128 v[190:193], v244 offset:1024
	ds_read_b128 v[170:173], v244 offset:2048
	ds_read_b128 v[186:189], v244 offset:3072
	ds_read_b128 v[166:169], v244 offset:4096
	ds_read_b128 v[182:185], v244 offset:5120
	ds_read_b128 v[162:165], v244 offset:6144
	ds_read_b128 v[178:181], v244 offset:7168
	global_load_lds_dwordx4 v[246:247], off
	v_lshl_add_u64 v[246:247], v[236:237], 0, s[80:81]
	s_add_i32 m0, s8, 0xe000
	s_nop 0
	global_load_lds_dwordx4 v[246:247], off
	s_waitcnt vmcnt(8)
	s_waitcnt lgkmcnt(0)
	s_barrier
	s_setprio 1
	s_waitcnt lgkmcnt(0)
	v_mfma_f32_16x16x32_bf16 v[118:121], v[146:149], v[174:177], v[118:121]
	v_mfma_f32_16x16x32_bf16 v[126:129], v[154:157], v[174:177], v[126:129]
	v_mfma_f32_16x16x32_bf16 v[102:105], v[146:149], v[170:173], v[102:105]
	v_mfma_f32_16x16x32_bf16 v[110:113], v[154:157], v[170:173], v[110:113]
	v_mfma_f32_16x16x32_bf16 v[86:89], v[146:149], v[166:169], v[86:89]
	v_mfma_f32_16x16x32_bf16 v[94:97], v[154:157], v[166:169], v[94:97]
	v_mfma_f32_16x16x32_bf16 v[70:73], v[146:149], v[162:165], v[70:73]
	v_mfma_f32_16x16x32_bf16 v[78:81], v[154:157], v[162:165], v[78:81]
	v_mfma_f32_16x16x32_bf16 v[118:121], v[150:153], v[190:193], v[118:121]
	v_mfma_f32_16x16x32_bf16 v[126:129], v[158:161], v[190:193], v[126:129]
	v_mfma_f32_16x16x32_bf16 v[102:105], v[150:153], v[186:189], v[102:105]
	v_mfma_f32_16x16x32_bf16 v[110:113], v[158:161], v[186:189], v[110:113]
	v_mfma_f32_16x16x32_bf16 v[86:89], v[150:153], v[182:185], v[86:89]
	v_mfma_f32_16x16x32_bf16 v[94:97], v[158:161], v[182:185], v[94:97]
	v_mfma_f32_16x16x32_bf16 v[70:73], v[150:153], v[178:181], v[70:73]
	v_mfma_f32_16x16x32_bf16 v[78:81], v[158:161], v[178:181], v[78:81]
	s_setprio 0
	s_setprio 1
	v_mfma_f32_16x16x32_bf16 v[122:125], v[130:133], v[174:177], v[122:125]
	v_mfma_f32_16x16x32_bf16 v[114:117], v[138:141], v[174:177], v[114:117]
	v_mfma_f32_16x16x32_bf16 v[106:109], v[130:133], v[170:173], v[106:109]
	v_mfma_f32_16x16x32_bf16 v[98:101], v[138:141], v[170:173], v[98:101]
	v_mfma_f32_16x16x32_bf16 v[90:93], v[130:133], v[166:169], v[90:93]
	v_mfma_f32_16x16x32_bf16 v[82:85], v[138:141], v[166:169], v[82:85]
	v_mfma_f32_16x16x32_bf16 v[74:77], v[130:133], v[162:165], v[74:77]
	v_mfma_f32_16x16x32_bf16 v[66:69], v[138:141], v[162:165], v[66:69]
	v_mfma_f32_16x16x32_bf16 v[122:125], v[134:137], v[190:193], v[122:125]
	v_mfma_f32_16x16x32_bf16 v[114:117], v[142:145], v[190:193], v[114:117]
	v_mfma_f32_16x16x32_bf16 v[106:109], v[134:137], v[186:189], v[106:109]
	v_mfma_f32_16x16x32_bf16 v[98:101], v[142:145], v[186:189], v[98:101]
	v_mfma_f32_16x16x32_bf16 v[90:93], v[134:137], v[182:185], v[90:93]
	v_mfma_f32_16x16x32_bf16 v[82:85], v[142:145], v[182:185], v[82:85]
	v_mfma_f32_16x16x32_bf16 v[74:77], v[134:137], v[178:181], v[74:77]
	v_mfma_f32_16x16x32_bf16 v[66:69], v[142:145], v[178:181], v[66:69]
	s_setprio 0
	s_barrier
	v_cndmask_b32_e64 v246, 0, 1, s[50:51]
	v_cmp_ne_u32_e64 s[48:49], 1, v246
	s_andn2_b64 vcc, exec, s[50:51]
	s_cbranch_vccnz .LBB0_178
	ds_read_b128 v[174:177], v244 offset:16384
	ds_read_b128 v[190:193], v244 offset:17408
	ds_read_b128 v[170:173], v244 offset:18432
	ds_read_b128 v[186:189], v244 offset:19456
	ds_read_b128 v[166:169], v244 offset:20480
	ds_read_b128 v[182:185], v244 offset:21504
	ds_read_b128 v[162:165], v244 offset:22528
	ds_read_b128 v[178:181], v244 offset:23552

.LBB0_180:
	s_and_b64 vcc, s[46:47], s[86:87]
	v_cndmask_b32_e64 v131, v233, 0, vcc
	v_cndmask_b32_e32 v130, v232, v198, vcc
	v_lshl_add_u64 v[246:247], s[84:85], 0, v[130:131]
	s_barrier
	s_mov_b32 m0, s8
	s_nop 0
	global_load_lds_dwordx4 v194, s[98:99]
	s_mov_b32 m0, s13
	s_nop 0
	global_load_lds_dwordx4 v196, s[98:99]
	v_add_u32_e32 v130, 0x18000, v243
	v_add_u32_e32 v142, 0x1c000, v243
	ds_read_b128 v[146:149], v130
	ds_read_b128 v[150:153], v130 offset:1024
	ds_read_b128 v[154:157], v130 offset:2048
	ds_read_b128 v[158:161], v130 offset:3072
	ds_read_b128 v[130:133], v142
	ds_read_b128 v[134:137], v142 offset:1024
	ds_read_b128 v[138:141], v142 offset:2048
	ds_read_b128 v[142:145], v142 offset:3072
	s_mov_b32 m0, s14
	v_lshl_add_u64 v[248:249], v[246:247], 0, v[194:195]
	ds_read_b128 v[174:177], v244 offset:32768
	ds_read_b128 v[190:193], v244 offset:33792
	ds_read_b128 v[170:173], v244 offset:34816
	ds_read_b128 v[186:189], v244 offset:35840
	ds_read_b128 v[166:169], v244 offset:36864
	ds_read_b128 v[182:185], v244 offset:37888
	ds_read_b128 v[162:165], v244 offset:38912
	ds_read_b128 v[178:181], v244 offset:39936
	global_load_lds_dwordx4 v[248:249], off
	v_lshl_add_u64 v[246:247], v[246:247], 0, v[196:197]
	s_mov_b32 m0, s15
	s_nop 0
	global_load_lds_dwordx4 v[246:247], off
	s_waitcnt vmcnt(8)
	s_waitcnt lgkmcnt(0)
	s_barrier
	s_setprio 1
	s_waitcnt lgkmcnt(0)
	v_mfma_f32_16x16x32_bf16 v[118:121], v[146:149], v[174:177], v[118:121]
	v_mfma_f32_16x16x32_bf16 v[126:129], v[154:157], v[174:177], v[126:129]
	v_mfma_f32_16x16x32_bf16 v[102:105], v[146:149], v[170:173], v[102:105]
	v_mfma_f32_16x16x32_bf16 v[110:113], v[154:157], v[170:173], v[110:113]
	v_mfma_f32_16x16x32_bf16 v[86:89], v[146:149], v[166:169], v[86:89]
	v_mfma_f32_16x16x32_bf16 v[94:97], v[154:157], v[166:169], v[94:97]
	v_mfma_f32_16x16x32_bf16 v[70:73], v[146:149], v[162:165], v[70:73]
	v_mfma_f32_16x16x32_bf16 v[78:81], v[154:157], v[162:165], v[78:81]
	v_mfma_f32_16x16x32_bf16 v[118:121], v[150:153], v[190:193], v[118:121]
	v_mfma_f32_16x16x32_bf16 v[126:129], v[158:161], v[190:193], v[126:129]
	v_mfma_f32_16x16x32_bf16 v[102:105], v[150:153], v[186:189], v[102:105]
	v_mfma_f32_16x16x32_bf16 v[110:113], v[158:161], v[186:189], v[110:113]
	v_mfma_f32_16x16x32_bf16 v[86:89], v[150:153], v[182:185], v[86:89]
	v_mfma_f32_16x16x32_bf16 v[94:97], v[158:161], v[182:185], v[94:97]
	v_mfma_f32_16x16x32_bf16 v[70:73], v[150:153], v[178:181], v[70:73]
	v_mfma_f32_16x16x32_bf16 v[78:81], v[158:161], v[178:181], v[78:81]
	s_setprio 0
	s_setprio 1
	v_mfma_f32_16x16x32_bf16 v[122:125], v[130:133], v[174:177], v[122:125]
	v_mfma_f32_16x16x32_bf16 v[114:117], v[138:141], v[174:177], v[114:117]
	v_mfma_f32_16x16x32_bf16 v[106:109], v[130:133], v[170:173], v[106:109]
	v_mfma_f32_16x16x32_bf16 v[98:101], v[138:141], v[170:173], v[98:101]
	v_mfma_f32_16x16x32_bf16 v[90:93], v[130:133], v[166:169], v[90:93]
	v_mfma_f32_16x16x32_bf16 v[82:85], v[138:141], v[166:169], v[82:85]
	v_mfma_f32_16x16x32_bf16 v[74:77], v[130:133], v[162:165], v[74:77]
	v_mfma_f32_16x16x32_bf16 v[66:69], v[138:141], v[162:165], v[66:69]
	v_mfma_f32_16x16x32_bf16 v[122:125], v[134:137], v[190:193], v[122:125]
	v_mfma_f32_16x16x32_bf16 v[114:117], v[142:145], v[190:193], v[114:117]
	v_mfma_f32_16x16x32_bf16 v[106:109], v[134:137], v[186:189], v[106:109]
	v_mfma_f32_16x16x32_bf16 v[98:101], v[142:145], v[186:189], v[98:101]
	v_mfma_f32_16x16x32_bf16 v[90:93], v[134:137], v[182:185], v[90:93]
	v_mfma_f32_16x16x32_bf16 v[82:85], v[142:145], v[182:185], v[82:85]
	v_mfma_f32_16x16x32_bf16 v[74:77], v[134:137], v[178:181], v[74:77]
	v_mfma_f32_16x16x32_bf16 v[66:69], v[142:145], v[178:181], v[66:69]
	s_setprio 0
	s_barrier
	s_and_b64 vcc, exec, s[48:49]
	s_cbranch_vccnz .LBB0_182
	ds_read_b128 v[174:177], v244 offset:49152
	ds_read_b128 v[190:193], v244 offset:50176
	ds_read_b128 v[170:173], v244 offset:51200
	ds_read_b128 v[186:189], v244 offset:52224
	ds_read_b128 v[166:169], v244 offset:53248
	ds_read_b128 v[182:185], v244 offset:54272
	ds_read_b128 v[162:165], v244 offset:55296
	ds_read_b128 v[178:181], v244 offset:56320

.LBB0_559:
	s_mov_b32 m0, s55
	s_nop 0
	global_load_lds_dwordx4 v194, s[100:101]
	s_mov_b32 m0, s67
	s_nop 0
	global_load_lds_dwordx4 v196, s[100:101]
	ds_read_b128 v[146:149], v227
	ds_read_b128 v[150:153], v227 offset:1024
	ds_read_b128 v[154:157], v227 offset:2048
	ds_read_b128 v[158:161], v227 offset:3072
	ds_read_b128 v[130:133], v228
	ds_read_b128 v[134:137], v228 offset:1024
	ds_read_b128 v[138:141], v228 offset:2048
	ds_read_b128 v[142:145], v228 offset:3072
	v_lshl_add_u64 v[234:235], v[216:217], 0, s[58:59]
	s_add_i32 m0, s8, 0xc000
	ds_read_b128 v[174:177], v229
	ds_read_b128 v[190:193], v229 offset:1024
	ds_read_b128 v[170:173], v229 offset:2048
	ds_read_b128 v[186:189], v229 offset:3072
	ds_read_b128 v[166:169], v229 offset:4096
	ds_read_b128 v[182:185], v229 offset:5120
	ds_read_b128 v[162:165], v229 offset:6144
	ds_read_b128 v[178:181], v229 offset:7168
	global_load_lds_dwordx4 v[234:235], off
	v_lshl_add_u64 v[234:235], v[218:219], 0, s[58:59]
	s_add_i32 m0, s8, 0xe000
	s_nop 0
	global_load_lds_dwordx4 v[234:235], off
	s_waitcnt vmcnt(8)
	s_waitcnt lgkmcnt(0)
	s_barrier
	s_setprio 1
	s_waitcnt lgkmcnt(0)
	v_mfma_f32_16x16x32_bf16 v[126:129], v[146:149], v[174:177], v[126:129]
	v_mfma_f32_16x16x32_bf16 v[122:125], v[154:157], v[174:177], v[122:125]
	v_mfma_f32_16x16x32_bf16 v[110:113], v[146:149], v[170:173], v[110:113]
	v_mfma_f32_16x16x32_bf16 v[106:109], v[154:157], v[170:173], v[106:109]
	v_mfma_f32_16x16x32_bf16 v[94:97], v[146:149], v[166:169], v[94:97]
	v_mfma_f32_16x16x32_bf16 v[90:93], v[154:157], v[166:169], v[90:93]
	v_mfma_f32_16x16x32_bf16 v[78:81], v[146:149], v[162:165], v[78:81]
	v_mfma_f32_16x16x32_bf16 v[74:77], v[154:157], v[162:165], v[74:77]
	v_mfma_f32_16x16x32_bf16 v[126:129], v[150:153], v[190:193], v[126:129]
	v_mfma_f32_16x16x32_bf16 v[122:125], v[158:161], v[190:193], v[122:125]
	v_mfma_f32_16x16x32_bf16 v[110:113], v[150:153], v[186:189], v[110:113]
	v_mfma_f32_16x16x32_bf16 v[106:109], v[158:161], v[186:189], v[106:109]
	v_mfma_f32_16x16x32_bf16 v[94:97], v[150:153], v[182:185], v[94:97]
	v_mfma_f32_16x16x32_bf16 v[90:93], v[158:161], v[182:185], v[90:93]
	v_mfma_f32_16x16x32_bf16 v[78:81], v[150:153], v[178:181], v[78:81]
	v_mfma_f32_16x16x32_bf16 v[74:77], v[158:161], v[178:181], v[74:77]
	s_setprio 0
	s_setprio 1
	v_mfma_f32_16x16x32_bf16 v[118:121], v[130:133], v[174:177], v[118:121]
	v_mfma_f32_16x16x32_bf16 v[114:117], v[138:141], v[174:177], v[114:117]
	v_mfma_f32_16x16x32_bf16 v[102:105], v[130:133], v[170:173], v[102:105]
	v_mfma_f32_16x16x32_bf16 v[98:101], v[138:141], v[170:173], v[98:101]
	v_mfma_f32_16x16x32_bf16 v[86:89], v[130:133], v[166:169], v[86:89]
	v_mfma_f32_16x16x32_bf16 v[82:85], v[138:141], v[166:169], v[82:85]
	v_mfma_f32_16x16x32_bf16 v[70:73], v[130:133], v[162:165], v[70:73]
	v_mfma_f32_16x16x32_bf16 v[66:69], v[138:141], v[162:165], v[66:69]
	v_mfma_f32_16x16x32_bf16 v[118:121], v[134:137], v[190:193], v[118:121]
	v_mfma_f32_16x16x32_bf16 v[114:117], v[142:145], v[190:193], v[114:117]
	v_mfma_f32_16x16x32_bf16 v[102:105], v[134:137], v[186:189], v[102:105]
	v_mfma_f32_16x16x32_bf16 v[98:101], v[142:145], v[186:189], v[98:101]
	v_mfma_f32_16x16x32_bf16 v[86:89], v[134:137], v[182:185], v[86:89]
	v_mfma_f32_16x16x32_bf16 v[82:85], v[142:145], v[182:185], v[82:85]
	v_mfma_f32_16x16x32_bf16 v[70:73], v[134:137], v[178:181], v[70:73]
	v_mfma_f32_16x16x32_bf16 v[66:69], v[142:145], v[178:181], v[66:69]
	s_setprio 0
	s_barrier
	v_cmp_ne_u32_e64 s[42:43], 1, v233
	s_andn2_b64 vcc, exec, s[44:45]
	s_cbranch_vccnz .LBB0_561
	ds_read_b128 v[174:177], v229 offset:16384
	ds_read_b128 v[190:193], v229 offset:17408
	ds_read_b128 v[170:173], v229 offset:18432
	ds_read_b128 v[186:189], v229 offset:19456
	ds_read_b128 v[166:169], v229 offset:20480
	ds_read_b128 v[182:185], v229 offset:21504
	ds_read_b128 v[162:165], v229 offset:22528
	ds_read_b128 v[178:181], v229 offset:23552

.LBB0_563:
	s_and_b64 vcc, s[40:41], s[68:69]
	v_cndmask_b32_e64 v131, v215, 0, vcc
	v_cndmask_b32_e32 v130, v214, v198, vcc
	v_lshl_add_u64 v[234:235], s[62:63], 0, v[130:131]
	s_barrier
	s_mov_b32 m0, s8
	s_nop 0
	global_load_lds_dwordx4 v194, s[98:99]
	s_mov_b32 m0, s13
	s_nop 0
	global_load_lds_dwordx4 v196, s[98:99]
	v_add_u32_e32 v130, 0x18000, v226
	v_add_u32_e32 v142, 0x1c000, v226
	ds_read_b128 v[146:149], v130
	ds_read_b128 v[150:153], v130 offset:1024
	ds_read_b128 v[154:157], v130 offset:2048
	ds_read_b128 v[158:161], v130 offset:3072
	ds_read_b128 v[130:133], v142
	ds_read_b128 v[134:137], v142 offset:1024
	ds_read_b128 v[138:141], v142 offset:2048
	ds_read_b128 v[142:145], v142 offset:3072
	s_mov_b32 m0, s14
	v_lshl_add_u64 v[236:237], v[234:235], 0, v[194:195]
	ds_read_b128 v[174:177], v229 offset:32768
	ds_read_b128 v[190:193], v229 offset:33792
	ds_read_b128 v[170:173], v229 offset:34816
	ds_read_b128 v[186:189], v229 offset:35840
	ds_read_b128 v[166:169], v229 offset:36864
	ds_read_b128 v[182:185], v229 offset:37888
	ds_read_b128 v[162:165], v229 offset:38912
	ds_read_b128 v[178:181], v229 offset:39936
	global_load_lds_dwordx4 v[236:237], off
	v_lshl_add_u64 v[234:235], v[234:235], 0, v[196:197]
	s_mov_b32 m0, s15
	s_nop 0
	global_load_lds_dwordx4 v[234:235], off
	s_waitcnt vmcnt(8)
	s_waitcnt lgkmcnt(0)
	s_barrier
	s_setprio 1
	s_waitcnt lgkmcnt(0)
	v_mfma_f32_16x16x32_bf16 v[126:129], v[146:149], v[174:177], v[126:129]
	v_mfma_f32_16x16x32_bf16 v[122:125], v[154:157], v[174:177], v[122:125]
	v_mfma_f32_16x16x32_bf16 v[110:113], v[146:149], v[170:173], v[110:113]
	v_mfma_f32_16x16x32_bf16 v[106:109], v[154:157], v[170:173], v[106:109]
	v_mfma_f32_16x16x32_bf16 v[94:97], v[146:149], v[166:169], v[94:97]
	v_mfma_f32_16x16x32_bf16 v[90:93], v[154:157], v[166:169], v[90:93]
	v_mfma_f32_16x16x32_bf16 v[78:81], v[146:149], v[162:165], v[78:81]
	v_mfma_f32_16x16x32_bf16 v[74:77], v[154:157], v[162:165], v[74:77]
	v_mfma_f32_16x16x32_bf16 v[126:129], v[150:153], v[190:193], v[126:129]
	v_mfma_f32_16x16x32_bf16 v[122:125], v[158:161], v[190:193], v[122:125]
	v_mfma_f32_16x16x32_bf16 v[110:113], v[150:153], v[186:189], v[110:113]
	v_mfma_f32_16x16x32_bf16 v[106:109], v[158:161], v[186:189], v[106:109]
	v_mfma_f32_16x16x32_bf16 v[94:97], v[150:153], v[182:185], v[94:97]
	v_mfma_f32_16x16x32_bf16 v[90:93], v[158:161], v[182:185], v[90:93]
	v_mfma_f32_16x16x32_bf16 v[78:81], v[150:153], v[178:181], v[78:81]
	v_mfma_f32_16x16x32_bf16 v[74:77], v[158:161], v[178:181], v[74:77]
	s_setprio 0
	s_setprio 1
	v_mfma_f32_16x16x32_bf16 v[118:121], v[130:133], v[174:177], v[118:121]
	v_mfma_f32_16x16x32_bf16 v[114:117], v[138:141], v[174:177], v[114:117]
	v_mfma_f32_16x16x32_bf16 v[102:105], v[130:133], v[170:173], v[102:105]
	v_mfma_f32_16x16x32_bf16 v[98:101], v[138:141], v[170:173], v[98:101]
	v_mfma_f32_16x16x32_bf16 v[86:89], v[130:133], v[166:169], v[86:89]
	v_mfma_f32_16x16x32_bf16 v[82:85], v[138:141], v[166:169], v[82:85]
	v_mfma_f32_16x16x32_bf16 v[70:73], v[130:133], v[162:165], v[70:73]
	v_mfma_f32_16x16x32_bf16 v[66:69], v[138:141], v[162:165], v[66:69]
	v_mfma_f32_16x16x32_bf16 v[118:121], v[134:137], v[190:193], v[118:121]
	v_mfma_f32_16x16x32_bf16 v[114:117], v[142:145], v[190:193], v[114:117]
	v_mfma_f32_16x16x32_bf16 v[102:105], v[134:137], v[186:189], v[102:105]
	v_mfma_f32_16x16x32_bf16 v[98:101], v[142:145], v[186:189], v[98:101]
	v_mfma_f32_16x16x32_bf16 v[86:89], v[134:137], v[182:185], v[86:89]
	v_mfma_f32_16x16x32_bf16 v[82:85], v[142:145], v[182:185], v[82:85]
	v_mfma_f32_16x16x32_bf16 v[70:73], v[134:137], v[178:181], v[70:73]
	v_mfma_f32_16x16x32_bf16 v[66:69], v[142:145], v[178:181], v[66:69]
	s_setprio 0
	s_barrier
	s_and_b64 vcc, exec, s[42:43]
	s_cbranch_vccnz .LBB0_565
	ds_read_b128 v[174:177], v229 offset:49152
	ds_read_b128 v[190:193], v229 offset:50176
	ds_read_b128 v[170:173], v229 offset:51200
	ds_read_b128 v[186:189], v229 offset:52224
	ds_read_b128 v[166:169], v229 offset:53248
	ds_read_b128 v[182:185], v229 offset:54272
	ds_read_b128 v[162:165], v229 offset:55296
	ds_read_b128 v[178:181], v229 offset:56320

.LBB0_903:
	s_mov_b32 m0, s23
	s_nop 0
	global_load_lds_dwordx4 v194, s[100:101]
	s_mov_b32 m0, s31
	s_nop 0
	global_load_lds_dwordx4 v196, s[100:101]
	ds_read_b128 v[146:149], v225
	ds_read_b128 v[150:153], v225 offset:1024
	ds_read_b128 v[154:157], v225 offset:2048
	ds_read_b128 v[158:161], v225 offset:3072
	ds_read_b128 v[130:133], v227
	ds_read_b128 v[134:137], v227 offset:1024
	ds_read_b128 v[138:141], v227 offset:2048
	ds_read_b128 v[142:145], v227 offset:3072
	v_lshl_add_u64 v[234:235], v[210:211], 0, s[62:63]
	s_add_i32 m0, s8, 0xc000
	ds_read_b128 v[174:177], v228
	ds_read_b128 v[190:193], v228 offset:1024
	ds_read_b128 v[170:173], v228 offset:2048
	ds_read_b128 v[186:189], v228 offset:3072
	ds_read_b128 v[166:169], v228 offset:4096
	ds_read_b128 v[182:185], v228 offset:5120
	ds_read_b128 v[162:165], v228 offset:6144
	ds_read_b128 v[178:181], v228 offset:7168
	global_load_lds_dwordx4 v[234:235], off
	v_lshl_add_u64 v[234:235], v[212:213], 0, s[62:63]
	s_add_i32 m0, s8, 0xe000
	s_nop 0
	global_load_lds_dwordx4 v[234:235], off
	s_waitcnt vmcnt(8)
	s_waitcnt lgkmcnt(0)
	s_barrier
	s_setprio 1
	s_waitcnt lgkmcnt(0)
	v_mfma_f32_16x16x32_bf16 v[126:129], v[146:149], v[174:177], v[126:129]
	v_mfma_f32_16x16x32_bf16 v[122:125], v[154:157], v[174:177], v[122:125]
	v_mfma_f32_16x16x32_bf16 v[118:121], v[146:149], v[170:173], v[118:121]
	v_mfma_f32_16x16x32_bf16 v[114:117], v[154:157], v[170:173], v[114:117]
	v_mfma_f32_16x16x32_bf16 v[110:113], v[146:149], v[166:169], v[110:113]
	v_mfma_f32_16x16x32_bf16 v[106:109], v[154:157], v[166:169], v[106:109]
	v_mfma_f32_16x16x32_bf16 v[102:105], v[146:149], v[162:165], v[102:105]
	v_mfma_f32_16x16x32_bf16 v[98:101], v[154:157], v[162:165], v[98:101]
	v_mfma_f32_16x16x32_bf16 v[126:129], v[150:153], v[190:193], v[126:129]
	v_mfma_f32_16x16x32_bf16 v[122:125], v[158:161], v[190:193], v[122:125]
	v_mfma_f32_16x16x32_bf16 v[118:121], v[150:153], v[186:189], v[118:121]
	v_mfma_f32_16x16x32_bf16 v[114:117], v[158:161], v[186:189], v[114:117]
	v_mfma_f32_16x16x32_bf16 v[110:113], v[150:153], v[182:185], v[110:113]
	v_mfma_f32_16x16x32_bf16 v[106:109], v[158:161], v[182:185], v[106:109]
	v_mfma_f32_16x16x32_bf16 v[102:105], v[150:153], v[178:181], v[102:105]
	v_mfma_f32_16x16x32_bf16 v[98:101], v[158:161], v[178:181], v[98:101]
	s_setprio 0
	s_setprio 1
	v_mfma_f32_16x16x32_bf16 v[94:97], v[130:133], v[174:177], v[94:97]
	v_mfma_f32_16x16x32_bf16 v[90:93], v[138:141], v[174:177], v[90:93]
	v_mfma_f32_16x16x32_bf16 v[86:89], v[130:133], v[170:173], v[86:89]
	v_mfma_f32_16x16x32_bf16 v[82:85], v[138:141], v[170:173], v[82:85]
	v_mfma_f32_16x16x32_bf16 v[78:81], v[130:133], v[166:169], v[78:81]
	v_mfma_f32_16x16x32_bf16 v[74:77], v[138:141], v[166:169], v[74:77]
	v_mfma_f32_16x16x32_bf16 v[70:73], v[130:133], v[162:165], v[70:73]
	v_mfma_f32_16x16x32_bf16 v[66:69], v[138:141], v[162:165], v[66:69]
	v_mfma_f32_16x16x32_bf16 v[94:97], v[134:137], v[190:193], v[94:97]
	v_mfma_f32_16x16x32_bf16 v[90:93], v[142:145], v[190:193], v[90:93]
	v_mfma_f32_16x16x32_bf16 v[86:89], v[134:137], v[186:189], v[86:89]
	v_mfma_f32_16x16x32_bf16 v[82:85], v[142:145], v[186:189], v[82:85]
	v_mfma_f32_16x16x32_bf16 v[78:81], v[134:137], v[182:185], v[78:81]
	v_mfma_f32_16x16x32_bf16 v[74:77], v[142:145], v[182:185], v[74:77]
	v_mfma_f32_16x16x32_bf16 v[70:73], v[134:137], v[178:181], v[70:73]
	v_mfma_f32_16x16x32_bf16 v[66:69], v[142:145], v[178:181], v[66:69]
	s_setprio 0
	s_barrier
	v_cmp_ne_u32_e64 s[42:43], 1, v233
	s_andn2_b64 vcc, exec, s[44:45]
	s_cbranch_vccnz .LBB0_905
	ds_read_b128 v[174:177], v228 offset:16384
	ds_read_b128 v[190:193], v228 offset:17408
	ds_read_b128 v[170:173], v228 offset:18432
	ds_read_b128 v[186:189], v228 offset:19456
	ds_read_b128 v[166:169], v228 offset:20480
	ds_read_b128 v[182:185], v228 offset:21504
	ds_read_b128 v[162:165], v228 offset:22528
	ds_read_b128 v[178:181], v228 offset:23552

.LBB0_907:
	s_and_b64 vcc, s[40:41], s[72:73]
	v_cndmask_b32_e64 v131, v209, 0, vcc
	v_cndmask_b32_e32 v130, v208, v198, vcc
	v_lshl_add_u64 v[234:235], s[70:71], 0, v[130:131]
	s_barrier
	s_mov_b32 m0, s8
	s_nop 0
	global_load_lds_dwordx4 v194, s[98:99]
	s_mov_b32 m0, s13
	s_nop 0
	global_load_lds_dwordx4 v196, s[98:99]
	v_add_u32_e32 v130, 0x18000, v224
	v_add_u32_e32 v142, 0x1c000, v224
	ds_read_b128 v[146:149], v130
	ds_read_b128 v[150:153], v130 offset:1024
	ds_read_b128 v[154:157], v130 offset:2048
	ds_read_b128 v[158:161], v130 offset:3072
	ds_read_b128 v[130:133], v142
	ds_read_b128 v[134:137], v142 offset:1024
	ds_read_b128 v[138:141], v142 offset:2048
	ds_read_b128 v[142:145], v142 offset:3072
	s_mov_b32 m0, s14
	v_lshl_add_u64 v[236:237], v[234:235], 0, v[194:195]
	ds_read_b128 v[174:177], v228 offset:32768
	ds_read_b128 v[190:193], v228 offset:33792
	ds_read_b128 v[170:173], v228 offset:34816
	ds_read_b128 v[186:189], v228 offset:35840
	ds_read_b128 v[166:169], v228 offset:36864
	ds_read_b128 v[182:185], v228 offset:37888
	ds_read_b128 v[162:165], v228 offset:38912
	ds_read_b128 v[178:181], v228 offset:39936
	global_load_lds_dwordx4 v[236:237], off
	v_lshl_add_u64 v[234:235], v[234:235], 0, v[196:197]
	s_mov_b32 m0, s15
	s_nop 0
	global_load_lds_dwordx4 v[234:235], off
	s_waitcnt vmcnt(8)
	s_waitcnt lgkmcnt(0)
	s_barrier
	s_setprio 1
	s_waitcnt lgkmcnt(0)
	v_mfma_f32_16x16x32_bf16 v[126:129], v[146:149], v[174:177], v[126:129]
	v_mfma_f32_16x16x32_bf16 v[122:125], v[154:157], v[174:177], v[122:125]
	v_mfma_f32_16x16x32_bf16 v[118:121], v[146:149], v[170:173], v[118:121]
	v_mfma_f32_16x16x32_bf16 v[114:117], v[154:157], v[170:173], v[114:117]
	v_mfma_f32_16x16x32_bf16 v[110:113], v[146:149], v[166:169], v[110:113]
	v_mfma_f32_16x16x32_bf16 v[106:109], v[154:157], v[166:169], v[106:109]
	v_mfma_f32_16x16x32_bf16 v[102:105], v[146:149], v[162:165], v[102:105]
	v_mfma_f32_16x16x32_bf16 v[98:101], v[154:157], v[162:165], v[98:101]
	v_mfma_f32_16x16x32_bf16 v[126:129], v[150:153], v[190:193], v[126:129]
	v_mfma_f32_16x16x32_bf16 v[122:125], v[158:161], v[190:193], v[122:125]
	v_mfma_f32_16x16x32_bf16 v[118:121], v[150:153], v[186:189], v[118:121]
	v_mfma_f32_16x16x32_bf16 v[114:117], v[158:161], v[186:189], v[114:117]
	v_mfma_f32_16x16x32_bf16 v[110:113], v[150:153], v[182:185], v[110:113]
	v_mfma_f32_16x16x32_bf16 v[106:109], v[158:161], v[182:185], v[106:109]
	v_mfma_f32_16x16x32_bf16 v[102:105], v[150:153], v[178:181], v[102:105]
	v_mfma_f32_16x16x32_bf16 v[98:101], v[158:161], v[178:181], v[98:101]
	s_setprio 0
	s_setprio 1
	v_mfma_f32_16x16x32_bf16 v[94:97], v[130:133], v[174:177], v[94:97]
	v_mfma_f32_16x16x32_bf16 v[90:93], v[138:141], v[174:177], v[90:93]
	v_mfma_f32_16x16x32_bf16 v[86:89], v[130:133], v[170:173], v[86:89]
	v_mfma_f32_16x16x32_bf16 v[82:85], v[138:141], v[170:173], v[82:85]
	v_mfma_f32_16x16x32_bf16 v[78:81], v[130:133], v[166:169], v[78:81]
	v_mfma_f32_16x16x32_bf16 v[74:77], v[138:141], v[166:169], v[74:77]
	v_mfma_f32_16x16x32_bf16 v[70:73], v[130:133], v[162:165], v[70:73]
	v_mfma_f32_16x16x32_bf16 v[66:69], v[138:141], v[162:165], v[66:69]
	v_mfma_f32_16x16x32_bf16 v[94:97], v[134:137], v[190:193], v[94:97]
	v_mfma_f32_16x16x32_bf16 v[90:93], v[142:145], v[190:193], v[90:93]
	v_mfma_f32_16x16x32_bf16 v[86:89], v[134:137], v[186:189], v[86:89]
	v_mfma_f32_16x16x32_bf16 v[82:85], v[142:145], v[186:189], v[82:85]
	v_mfma_f32_16x16x32_bf16 v[78:81], v[134:137], v[182:185], v[78:81]
	v_mfma_f32_16x16x32_bf16 v[74:77], v[142:145], v[182:185], v[74:77]
	v_mfma_f32_16x16x32_bf16 v[70:73], v[134:137], v[178:181], v[70:73]
	v_mfma_f32_16x16x32_bf16 v[66:69], v[142:145], v[178:181], v[66:69]
	s_setprio 0
	s_barrier
	s_and_b64 vcc, exec, s[42:43]
	s_cbranch_vccnz .LBB0_909
	ds_read_b128 v[174:177], v228 offset:49152
	ds_read_b128 v[190:193], v228 offset:50176
	ds_read_b128 v[170:173], v228 offset:51200
	ds_read_b128 v[186:189], v228 offset:52224
	ds_read_b128 v[166:169], v228 offset:53248
	ds_read_b128 v[182:185], v228 offset:54272
	ds_read_b128 v[162:165], v228 offset:55296
	ds_read_b128 v[178:181], v228 offset:56320

.LBB0_1289:
	s_mov_b32 m0, s27
	s_nop 0
	global_load_lds_dwordx4 v194, s[100:101]
	s_mov_b32 m0, s54
	s_nop 0
	global_load_lds_dwordx4 v196, s[100:101]
	v_add_u32_e32 v142, 0x14000, v229
	ds_read_b128 v[146:149], v230
	ds_read_b128 v[150:153], v230 offset:1024
	ds_read_b128 v[154:157], v230 offset:2048
	ds_read_b128 v[158:161], v230 offset:3072
	ds_read_b128 v[130:133], v142
	ds_read_b128 v[134:137], v142 offset:1024
	ds_read_b128 v[138:141], v142 offset:2048
	ds_read_b128 v[142:145], v142 offset:3072
	v_lshl_add_u64 v[234:235], v[222:223], 0, s[48:49]
	s_add_i32 m0, s8, 0xc000
	ds_read_b128 v[174:177], v231
	ds_read_b128 v[190:193], v231 offset:1024
	ds_read_b128 v[170:173], v231 offset:2048
	ds_read_b128 v[186:189], v231 offset:3072
	ds_read_b128 v[166:169], v231 offset:4096
	ds_read_b128 v[182:185], v231 offset:5120
	ds_read_b128 v[162:165], v231 offset:6144
	ds_read_b128 v[178:181], v231 offset:7168
	global_load_lds_dwordx4 v[234:235], off
	v_lshl_add_u64 v[234:235], v[224:225], 0, s[48:49]
	s_add_i32 m0, s8, 0xe000
	s_nop 0
	global_load_lds_dwordx4 v[234:235], off
	s_waitcnt vmcnt(8)
	s_waitcnt lgkmcnt(0)
	s_barrier
	s_setprio 1
	s_waitcnt lgkmcnt(0)
	v_mfma_f32_16x16x32_bf16 v[126:129], v[146:149], v[174:177], v[126:129]
	v_mfma_f32_16x16x32_bf16 v[122:125], v[154:157], v[174:177], v[122:125]
	v_mfma_f32_16x16x32_bf16 v[118:121], v[146:149], v[170:173], v[118:121]
	v_mfma_f32_16x16x32_bf16 v[110:113], v[154:157], v[170:173], v[110:113]
	v_mfma_f32_16x16x32_bf16 v[102:105], v[146:149], v[166:169], v[102:105]
	v_mfma_f32_16x16x32_bf16 v[94:97], v[154:157], v[166:169], v[94:97]
	v_mfma_f32_16x16x32_bf16 v[86:89], v[146:149], v[162:165], v[86:89]
	v_mfma_f32_16x16x32_bf16 v[78:81], v[154:157], v[162:165], v[78:81]
	v_mfma_f32_16x16x32_bf16 v[126:129], v[150:153], v[190:193], v[126:129]
	v_mfma_f32_16x16x32_bf16 v[122:125], v[158:161], v[190:193], v[122:125]
	v_mfma_f32_16x16x32_bf16 v[118:121], v[150:153], v[186:189], v[118:121]
	v_mfma_f32_16x16x32_bf16 v[110:113], v[158:161], v[186:189], v[110:113]
	v_mfma_f32_16x16x32_bf16 v[102:105], v[150:153], v[182:185], v[102:105]
	v_mfma_f32_16x16x32_bf16 v[94:97], v[158:161], v[182:185], v[94:97]
	v_mfma_f32_16x16x32_bf16 v[86:89], v[150:153], v[178:181], v[86:89]
	v_mfma_f32_16x16x32_bf16 v[78:81], v[158:161], v[178:181], v[78:81]
	s_setprio 0
	s_setprio 1
	v_mfma_f32_16x16x32_bf16 v[114:117], v[130:133], v[174:177], v[114:117]
	v_mfma_f32_16x16x32_bf16 v[106:109], v[138:141], v[174:177], v[106:109]
	v_mfma_f32_16x16x32_bf16 v[98:101], v[130:133], v[170:173], v[98:101]
	v_mfma_f32_16x16x32_bf16 v[90:93], v[138:141], v[170:173], v[90:93]
	v_mfma_f32_16x16x32_bf16 v[82:85], v[130:133], v[166:169], v[82:85]
	v_mfma_f32_16x16x32_bf16 v[74:77], v[138:141], v[166:169], v[74:77]
	v_mfma_f32_16x16x32_bf16 v[70:73], v[130:133], v[162:165], v[70:73]
	v_mfma_f32_16x16x32_bf16 v[66:69], v[138:141], v[162:165], v[66:69]
	v_mfma_f32_16x16x32_bf16 v[114:117], v[134:137], v[190:193], v[114:117]
	v_mfma_f32_16x16x32_bf16 v[106:109], v[142:145], v[190:193], v[106:109]
	v_mfma_f32_16x16x32_bf16 v[98:101], v[134:137], v[186:189], v[98:101]
	v_mfma_f32_16x16x32_bf16 v[90:93], v[142:145], v[186:189], v[90:93]
	v_mfma_f32_16x16x32_bf16 v[82:85], v[134:137], v[182:185], v[82:85]
	v_mfma_f32_16x16x32_bf16 v[74:77], v[142:145], v[182:185], v[74:77]
	v_mfma_f32_16x16x32_bf16 v[70:73], v[134:137], v[178:181], v[70:73]
	v_mfma_f32_16x16x32_bf16 v[66:69], v[142:145], v[178:181], v[66:69]
	s_setprio 0
	s_barrier
	v_cndmask_b32_e64 v233, 0, 1, s[40:41]
	v_cmp_ne_u32_e64 s[42:43], 1, v233
	s_andn2_b64 vcc, exec, s[40:41]
	s_cbranch_vccnz .LBB0_1291
	ds_read_b128 v[174:177], v231 offset:16384
	ds_read_b128 v[190:193], v231 offset:17408
	ds_read_b128 v[170:173], v231 offset:18432
	ds_read_b128 v[186:189], v231 offset:19456
	ds_read_b128 v[166:169], v231 offset:20480
	ds_read_b128 v[182:185], v231 offset:21504
	ds_read_b128 v[162:165], v231 offset:22528
	ds_read_b128 v[178:181], v231 offset:23552

.LBB0_1293:
	s_and_b64 vcc, s[34:35], s[58:59]
	v_cndmask_b32_e64 v131, v221, 0, vcc
	v_cndmask_b32_e32 v130, v220, v198, vcc
	v_lshl_add_u64 v[234:235], s[56:57], 0, v[130:131]
	s_barrier
	s_mov_b32 m0, s8
	s_nop 0
	global_load_lds_dwordx4 v194, s[98:99]
	s_mov_b32 m0, s13
	s_nop 0
	global_load_lds_dwordx4 v196, s[98:99]
	v_add_u32_e32 v130, 0x18000, v229
	v_add_u32_e32 v142, 0x1c000, v229
	ds_read_b128 v[146:149], v130
	ds_read_b128 v[150:153], v130 offset:1024
	ds_read_b128 v[154:157], v130 offset:2048
	ds_read_b128 v[158:161], v130 offset:3072
	ds_read_b128 v[130:133], v142
	ds_read_b128 v[134:137], v142 offset:1024
	ds_read_b128 v[138:141], v142 offset:2048
	ds_read_b128 v[142:145], v142 offset:3072
	s_mov_b32 m0, s14
	v_lshl_add_u64 v[236:237], v[234:235], 0, v[194:195]
	ds_read_b128 v[174:177], v231 offset:32768
	ds_read_b128 v[190:193], v231 offset:33792
	ds_read_b128 v[170:173], v231 offset:34816
	ds_read_b128 v[186:189], v231 offset:35840
	ds_read_b128 v[166:169], v231 offset:36864
	ds_read_b128 v[182:185], v231 offset:37888
	ds_read_b128 v[162:165], v231 offset:38912
	ds_read_b128 v[178:181], v231 offset:39936
	global_load_lds_dwordx4 v[236:237], off
	v_lshl_add_u64 v[234:235], v[234:235], 0, v[196:197]
	s_mov_b32 m0, s15
	s_nop 0
	global_load_lds_dwordx4 v[234:235], off
	s_waitcnt vmcnt(8)
	s_waitcnt lgkmcnt(0)
	s_barrier
	s_setprio 1
	s_waitcnt lgkmcnt(0)
	v_mfma_f32_16x16x32_bf16 v[126:129], v[146:149], v[174:177], v[126:129]
	v_mfma_f32_16x16x32_bf16 v[122:125], v[154:157], v[174:177], v[122:125]
	v_mfma_f32_16x16x32_bf16 v[118:121], v[146:149], v[170:173], v[118:121]
	v_mfma_f32_16x16x32_bf16 v[110:113], v[154:157], v[170:173], v[110:113]
	v_mfma_f32_16x16x32_bf16 v[102:105], v[146:149], v[166:169], v[102:105]
	v_mfma_f32_16x16x32_bf16 v[94:97], v[154:157], v[166:169], v[94:97]
	v_mfma_f32_16x16x32_bf16 v[86:89], v[146:149], v[162:165], v[86:89]
	v_mfma_f32_16x16x32_bf16 v[78:81], v[154:157], v[162:165], v[78:81]
	v_mfma_f32_16x16x32_bf16 v[126:129], v[150:153], v[190:193], v[126:129]
	v_mfma_f32_16x16x32_bf16 v[122:125], v[158:161], v[190:193], v[122:125]
	v_mfma_f32_16x16x32_bf16 v[118:121], v[150:153], v[186:189], v[118:121]
	v_mfma_f32_16x16x32_bf16 v[110:113], v[158:161], v[186:189], v[110:113]
	v_mfma_f32_16x16x32_bf16 v[102:105], v[150:153], v[182:185], v[102:105]
	v_mfma_f32_16x16x32_bf16 v[94:97], v[158:161], v[182:185], v[94:97]
	v_mfma_f32_16x16x32_bf16 v[86:89], v[150:153], v[178:181], v[86:89]
	v_mfma_f32_16x16x32_bf16 v[78:81], v[158:161], v[178:181], v[78:81]
	s_setprio 0
	s_setprio 1
	v_mfma_f32_16x16x32_bf16 v[114:117], v[130:133], v[174:177], v[114:117]
	v_mfma_f32_16x16x32_bf16 v[106:109], v[138:141], v[174:177], v[106:109]
	v_mfma_f32_16x16x32_bf16 v[98:101], v[130:133], v[170:173], v[98:101]
	v_mfma_f32_16x16x32_bf16 v[90:93], v[138:141], v[170:173], v[90:93]
	v_mfma_f32_16x16x32_bf16 v[82:85], v[130:133], v[166:169], v[82:85]
	v_mfma_f32_16x16x32_bf16 v[74:77], v[138:141], v[166:169], v[74:77]
	v_mfma_f32_16x16x32_bf16 v[70:73], v[130:133], v[162:165], v[70:73]
	v_mfma_f32_16x16x32_bf16 v[66:69], v[138:141], v[162:165], v[66:69]
	v_mfma_f32_16x16x32_bf16 v[114:117], v[134:137], v[190:193], v[114:117]
	v_mfma_f32_16x16x32_bf16 v[106:109], v[142:145], v[190:193], v[106:109]
	v_mfma_f32_16x16x32_bf16 v[98:101], v[134:137], v[186:189], v[98:101]
	v_mfma_f32_16x16x32_bf16 v[90:93], v[142:145], v[186:189], v[90:93]
	v_mfma_f32_16x16x32_bf16 v[82:85], v[134:137], v[182:185], v[82:85]
	v_mfma_f32_16x16x32_bf16 v[74:77], v[142:145], v[182:185], v[74:77]
	v_mfma_f32_16x16x32_bf16 v[70:73], v[134:137], v[178:181], v[70:73]
	v_mfma_f32_16x16x32_bf16 v[66:69], v[142:145], v[178:181], v[66:69]
	s_setprio 0
	s_barrier
	s_and_b64 vcc, exec, s[42:43]
	s_cbranch_vccnz .LBB0_1295
	ds_read_b128 v[174:177], v231 offset:49152
	ds_read_b128 v[190:193], v231 offset:50176
	ds_read_b128 v[170:173], v231 offset:51200
	ds_read_b128 v[186:189], v231 offset:52224
	ds_read_b128 v[166:169], v231 offset:53248
	ds_read_b128 v[182:185], v231 offset:54272
	ds_read_b128 v[162:165], v231 offset:55296
	ds_read_b128 v[178:181], v231 offset:56320

.LBB0_1612:
	s_mov_b32 m0, s54
	s_nop 0
	global_load_lds_dwordx4 v194, s[100:101]
	s_mov_b32 m0, s55
	s_nop 0
	global_load_lds_dwordx4 v196, s[100:101]
	v_add_u32_e32 v1, 0x10000, v232
	ds_read_b128 v[146:149], v1
	ds_read_b128 v[150:153], v1 offset:1024
	ds_read_b128 v[154:157], v1 offset:2048
	ds_read_b128 v[158:161], v1 offset:3072
	v_add_u32_e32 v1, 0x14000, v232
	ds_read_b128 v[130:133], v1
	ds_read_b128 v[134:137], v1 offset:1024
	ds_read_b128 v[138:141], v1 offset:2048
	ds_read_b128 v[142:145], v1 offset:3072
	v_lshl_add_u64 v[236:237], v[226:227], 0, s[48:49]
	s_add_i32 m0, s9, 0xc000
	ds_read_b128 v[174:177], v233
	ds_read_b128 v[190:193], v233 offset:1024
	ds_read_b128 v[170:173], v233 offset:2048
	ds_read_b128 v[186:189], v233 offset:3072
	ds_read_b128 v[166:169], v233 offset:4096
	ds_read_b128 v[182:185], v233 offset:5120
	ds_read_b128 v[162:165], v233 offset:6144
	ds_read_b128 v[178:181], v233 offset:7168
	global_load_lds_dwordx4 v[236:237], off
	v_lshl_add_u64 v[236:237], v[228:229], 0, s[48:49]
	s_add_i32 m0, s9, 0xe000
	s_nop 0
	global_load_lds_dwordx4 v[236:237], off
	s_waitcnt vmcnt(8)
	s_waitcnt lgkmcnt(0)
	s_barrier
	s_setprio 1
	s_waitcnt lgkmcnt(0)
	v_mfma_f32_16x16x32_bf16 v[126:129], v[146:149], v[174:177], v[126:129]
	v_mfma_f32_16x16x32_bf16 v[122:125], v[154:157], v[174:177], v[122:125]
	v_mfma_f32_16x16x32_bf16 v[118:121], v[146:149], v[170:173], v[118:121]
	v_mfma_f32_16x16x32_bf16 v[110:113], v[154:157], v[170:173], v[110:113]
	v_mfma_f32_16x16x32_bf16 v[102:105], v[146:149], v[166:169], v[102:105]
	v_mfma_f32_16x16x32_bf16 v[94:97], v[154:157], v[166:169], v[94:97]
	v_mfma_f32_16x16x32_bf16 v[86:89], v[146:149], v[162:165], v[86:89]
	v_mfma_f32_16x16x32_bf16 v[78:81], v[154:157], v[162:165], v[78:81]
	v_mfma_f32_16x16x32_bf16 v[126:129], v[150:153], v[190:193], v[126:129]
	v_mfma_f32_16x16x32_bf16 v[122:125], v[158:161], v[190:193], v[122:125]
	v_mfma_f32_16x16x32_bf16 v[118:121], v[150:153], v[186:189], v[118:121]
	v_mfma_f32_16x16x32_bf16 v[110:113], v[158:161], v[186:189], v[110:113]
	v_mfma_f32_16x16x32_bf16 v[102:105], v[150:153], v[182:185], v[102:105]
	v_mfma_f32_16x16x32_bf16 v[94:97], v[158:161], v[182:185], v[94:97]
	v_mfma_f32_16x16x32_bf16 v[86:89], v[150:153], v[178:181], v[86:89]
	v_mfma_f32_16x16x32_bf16 v[78:81], v[158:161], v[178:181], v[78:81]
	s_setprio 0
	s_setprio 1
	v_mfma_f32_16x16x32_bf16 v[114:117], v[130:133], v[174:177], v[114:117]
	v_mfma_f32_16x16x32_bf16 v[106:109], v[138:141], v[174:177], v[106:109]
	v_mfma_f32_16x16x32_bf16 v[98:101], v[130:133], v[170:173], v[98:101]
	v_mfma_f32_16x16x32_bf16 v[90:93], v[138:141], v[170:173], v[90:93]
	v_mfma_f32_16x16x32_bf16 v[82:85], v[130:133], v[166:169], v[82:85]
	v_mfma_f32_16x16x32_bf16 v[74:77], v[138:141], v[166:169], v[74:77]
	v_mfma_f32_16x16x32_bf16 v[70:73], v[130:133], v[162:165], v[70:73]
	v_mfma_f32_16x16x32_bf16 v[66:69], v[138:141], v[162:165], v[66:69]
	v_mfma_f32_16x16x32_bf16 v[114:117], v[134:137], v[190:193], v[114:117]
	v_mfma_f32_16x16x32_bf16 v[106:109], v[142:145], v[190:193], v[106:109]
	v_mfma_f32_16x16x32_bf16 v[98:101], v[134:137], v[186:189], v[98:101]
	v_mfma_f32_16x16x32_bf16 v[90:93], v[142:145], v[186:189], v[90:93]
	v_mfma_f32_16x16x32_bf16 v[82:85], v[134:137], v[182:185], v[82:85]
	v_mfma_f32_16x16x32_bf16 v[74:77], v[142:145], v[182:185], v[74:77]
	v_mfma_f32_16x16x32_bf16 v[70:73], v[134:137], v[178:181], v[70:73]
	v_mfma_f32_16x16x32_bf16 v[66:69], v[142:145], v[178:181], v[66:69]
	s_setprio 0
	s_barrier
	v_cndmask_b32_e64 v1, 0, 1, s[40:41]
	v_cmp_ne_u32_e64 s[42:43], 1, v1
	s_andn2_b64 vcc, exec, s[40:41]
	s_cbranch_vccnz .LBB0_1614
	ds_read_b128 v[174:177], v233 offset:16384
	ds_read_b128 v[190:193], v233 offset:17408
	ds_read_b128 v[170:173], v233 offset:18432
	ds_read_b128 v[186:189], v233 offset:19456
	ds_read_b128 v[166:169], v233 offset:20480
	ds_read_b128 v[182:185], v233 offset:21504
	ds_read_b128 v[162:165], v233 offset:22528
	ds_read_b128 v[178:181], v233 offset:23552

.LBB0_1616:
	s_and_b64 vcc, s[38:39], s[56:57]
	v_cndmask_b32_e64 v131, v225, 0, vcc
	v_cndmask_b32_e32 v130, v224, v198, vcc
	v_lshl_add_u64 v[236:237], s[52:53], 0, v[130:131]
	s_barrier
	s_mov_b32 m0, s9
	s_nop 0
	global_load_lds_dwordx4 v194, s[98:99]
	s_mov_b32 m0, s14
	s_nop 0
	global_load_lds_dwordx4 v196, s[98:99]
	v_add_u32_e32 v1, 0x18000, v232
	ds_read_b128 v[146:149], v1
	ds_read_b128 v[150:153], v1 offset:1024
	ds_read_b128 v[154:157], v1 offset:2048
	ds_read_b128 v[158:161], v1 offset:3072
	v_add_u32_e32 v1, 0x1c000, v232
	ds_read_b128 v[130:133], v1
	ds_read_b128 v[134:137], v1 offset:1024
	ds_read_b128 v[138:141], v1 offset:2048
	ds_read_b128 v[142:145], v1 offset:3072
	s_mov_b32 m0, s15
	v_lshl_add_u64 v[238:239], v[236:237], 0, v[194:195]
	ds_read_b128 v[174:177], v233 offset:32768
	ds_read_b128 v[190:193], v233 offset:33792
	ds_read_b128 v[170:173], v233 offset:34816
	ds_read_b128 v[186:189], v233 offset:35840
	ds_read_b128 v[166:169], v233 offset:36864
	ds_read_b128 v[182:185], v233 offset:37888
	ds_read_b128 v[162:165], v233 offset:38912
	ds_read_b128 v[178:181], v233 offset:39936
	global_load_lds_dwordx4 v[238:239], off
	v_lshl_add_u64 v[236:237], v[236:237], 0, v[196:197]
	s_mov_b32 m0, s16
	s_nop 0
	global_load_lds_dwordx4 v[236:237], off
	s_waitcnt vmcnt(8)
	s_waitcnt lgkmcnt(0)
	s_barrier
	s_setprio 1
	s_waitcnt lgkmcnt(0)
	v_mfma_f32_16x16x32_bf16 v[126:129], v[146:149], v[174:177], v[126:129]
	v_mfma_f32_16x16x32_bf16 v[122:125], v[154:157], v[174:177], v[122:125]
	v_mfma_f32_16x16x32_bf16 v[118:121], v[146:149], v[170:173], v[118:121]
	v_mfma_f32_16x16x32_bf16 v[110:113], v[154:157], v[170:173], v[110:113]
	v_mfma_f32_16x16x32_bf16 v[102:105], v[146:149], v[166:169], v[102:105]
	v_mfma_f32_16x16x32_bf16 v[94:97], v[154:157], v[166:169], v[94:97]
	v_mfma_f32_16x16x32_bf16 v[86:89], v[146:149], v[162:165], v[86:89]
	v_mfma_f32_16x16x32_bf16 v[78:81], v[154:157], v[162:165], v[78:81]
	v_mfma_f32_16x16x32_bf16 v[126:129], v[150:153], v[190:193], v[126:129]
	v_mfma_f32_16x16x32_bf16 v[122:125], v[158:161], v[190:193], v[122:125]
	v_mfma_f32_16x16x32_bf16 v[118:121], v[150:153], v[186:189], v[118:121]
	v_mfma_f32_16x16x32_bf16 v[110:113], v[158:161], v[186:189], v[110:113]
	v_mfma_f32_16x16x32_bf16 v[102:105], v[150:153], v[182:185], v[102:105]
	v_mfma_f32_16x16x32_bf16 v[94:97], v[158:161], v[182:185], v[94:97]
	v_mfma_f32_16x16x32_bf16 v[86:89], v[150:153], v[178:181], v[86:89]
	v_mfma_f32_16x16x32_bf16 v[78:81], v[158:161], v[178:181], v[78:81]
	s_setprio 0
	s_setprio 1
	v_mfma_f32_16x16x32_bf16 v[114:117], v[130:133], v[174:177], v[114:117]
	v_mfma_f32_16x16x32_bf16 v[106:109], v[138:141], v[174:177], v[106:109]
	v_mfma_f32_16x16x32_bf16 v[98:101], v[130:133], v[170:173], v[98:101]
	v_mfma_f32_16x16x32_bf16 v[90:93], v[138:141], v[170:173], v[90:93]
	v_mfma_f32_16x16x32_bf16 v[82:85], v[130:133], v[166:169], v[82:85]
	v_mfma_f32_16x16x32_bf16 v[74:77], v[138:141], v[166:169], v[74:77]
	v_mfma_f32_16x16x32_bf16 v[70:73], v[130:133], v[162:165], v[70:73]
	v_mfma_f32_16x16x32_bf16 v[66:69], v[138:141], v[162:165], v[66:69]
	v_mfma_f32_16x16x32_bf16 v[114:117], v[134:137], v[190:193], v[114:117]
	v_mfma_f32_16x16x32_bf16 v[106:109], v[142:145], v[190:193], v[106:109]
	v_mfma_f32_16x16x32_bf16 v[98:101], v[134:137], v[186:189], v[98:101]
	v_mfma_f32_16x16x32_bf16 v[90:93], v[142:145], v[186:189], v[90:93]
	v_mfma_f32_16x16x32_bf16 v[82:85], v[134:137], v[182:185], v[82:85]
	v_mfma_f32_16x16x32_bf16 v[74:77], v[142:145], v[182:185], v[74:77]
	v_mfma_f32_16x16x32_bf16 v[70:73], v[134:137], v[178:181], v[70:73]
	v_mfma_f32_16x16x32_bf16 v[66:69], v[142:145], v[178:181], v[66:69]
	s_setprio 0
	s_barrier
	s_and_b64 vcc, exec, s[42:43]
	s_cbranch_vccnz .LBB0_1618
	ds_read_b128 v[174:177], v233 offset:49152
	ds_read_b128 v[190:193], v233 offset:50176
	ds_read_b128 v[170:173], v233 offset:51200
	ds_read_b128 v[186:189], v233 offset:52224
	ds_read_b128 v[166:169], v233 offset:53248
	ds_read_b128 v[182:185], v233 offset:54272
	ds_read_b128 v[162:165], v233 offset:55296
	ds_read_b128 v[178:181], v233 offset:56320
